# gemm_sample_rows K loop staged through LDS with LDS-DMA in whole 128-byte lines (per-wave private region, source-side XOR swizzle), next K tile's DMA issued before the MFMAs
# speedup vs baseline: 1.0123x; 1.0123x over previous
; template <int NH>
; __device__ void gemm_sample_rows(const Params& p, const u16* __restrict__ A, const u16* __restrict__ Bt,
;                                  const float* __restrict__ resid, float* __restrict__ outf, unsigned char* smem, const int rep) {
;     ...
;     const u16* ap = A + (size_t)(m0 + l15) * K + w * 256 + 8 * g;
;     const u16* bp = Bt + (size_t)(n0 + l15) * K + w * 256 + 8 * g;
; #pragma unroll 2
;     for (int ks = 0; ks < 8; ++ks) {
;       bf16x8 af[4], bfr[4];
; #pragma unroll
;       for (int mf = 0; mf < 4; ++mf) af[mf] = *(const bf16x8*)(ap + (size_t)(mf * 16) * K + ks * 32);
; #pragma unroll
;       for (int nf = 0; nf < 4; ++nf) bfr[nf] = *(const bf16x8*)(bp + (size_t)(nf * 16) * K + ks * 32);
; #pragma unroll
;       for (int mf = 0; mf < 4; ++mf)
; #pragma unroll
;         for (int nf = 0; nf < 4; ++nf)
;           acc[mf][nf] = __builtin_amdgcn_mfma_f32_16x16x32_bf16(af[mf], bfr[nf], acc[mf][nf], 0, 0, 0);
;     }
.LBB0_730:
	v_readfirstlane_b32 s50, v66
	v_readfirstlane_b32 s51, v67
	s_add_u32 s50, s50, s21
	s_addc_u32 s51, s51, 0
	v_readfirstlane_b32 s52, v68
	v_readfirstlane_b32 s53, v69
	s_add_u32 s52, s52, s25
	s_addc_u32 s53, s53, 0
	v_readlane_b32 s54, v255, 6
	s_lshl_b32 s54, s54, 14
	v_mbcnt_lo_u32_b32 v240, -1, 0
	v_mbcnt_hi_u32_b32 v240, -1, v240
	v_lshrrev_b32_e32 v241, 3, v240
	v_lshlrev_b32_e32 v241, 12, v241
	v_and_b32_e32 v242, 7, v240
	v_lshrrev_b32_e32 v243, 4, v240
	v_xor_b32_e32 v244, v242, v243
	v_lshl_add_u32 v232, v244, 4, v241
	v_xor_b32_e32 v244, 4, v244
	v_lshl_add_u32 v233, v244, 4, v241
	v_add_u32_e32 v233, 0x8000, v233
	v_add_u32_e32 v234, 0x10000, v232
	v_add_u32_e32 v235, 0x10000, v233
	v_add_u32_e32 v236, 0x20000, v232
	v_add_u32_e32 v237, 0x20000, v233
	v_add_u32_e32 v238, 0x30000, v232
	v_add_u32_e32 v239, 0x30000, v233
	v_and_b32_e32 v245, 15, v240
	v_lshrrev_b32_e32 v246, 1, v245
	v_xor_b32_e32 v246, v243, v246
	v_lshlrev_b32_e32 v246, 4, v246
	v_lshl_add_u32 v246, v245, 7, v246
	v_add_u32_e32 v246, s54, v246
	v_xor_b32_e32 v247, 64, v246
	s_add_u32 m0, s54, 0x0
	s_nop 0
	global_load_lds_dwordx4 v232, s[50:51]
	s_add_u32 m0, s54, 0x400
	s_nop 0
	global_load_lds_dwordx4 v233, s[50:51]
	s_add_u32 m0, s54, 0x800
	s_nop 0
	global_load_lds_dwordx4 v234, s[50:51]
	s_add_u32 m0, s54, 0xc00
	s_nop 0
	global_load_lds_dwordx4 v235, s[50:51]
	s_add_u32 m0, s54, 0x1000
	s_nop 0
	global_load_lds_dwordx4 v236, s[50:51]
	s_add_u32 m0, s54, 0x1400
	s_nop 0
	global_load_lds_dwordx4 v237, s[50:51]
	s_add_u32 m0, s54, 0x1800
	s_nop 0
	global_load_lds_dwordx4 v238, s[50:51]
	s_add_u32 m0, s54, 0x1c00
	s_nop 0
	global_load_lds_dwordx4 v239, s[50:51]
	s_add_u32 m0, s54, 0x2000
	s_nop 0
	global_load_lds_dwordx4 v232, s[52:53]
	s_add_u32 m0, s54, 0x2400
	s_nop 0
	global_load_lds_dwordx4 v233, s[52:53]
	s_add_u32 m0, s54, 0x2800
	s_nop 0
	global_load_lds_dwordx4 v234, s[52:53]
	s_add_u32 m0, s54, 0x2c00
	s_nop 0
	global_load_lds_dwordx4 v235, s[52:53]
	s_add_u32 m0, s54, 0x3000
	s_nop 0
	global_load_lds_dwordx4 v236, s[52:53]
	s_add_u32 m0, s54, 0x3400
	s_nop 0
	global_load_lds_dwordx4 v237, s[52:53]
	s_add_u32 m0, s54, 0x3800
	s_nop 0
	global_load_lds_dwordx4 v238, s[52:53]
	s_add_u32 m0, s54, 0x3c00
	s_nop 0
	global_load_lds_dwordx4 v239, s[52:53]
	s_add_u32 s50, s50, 0x80
	s_addc_u32 s51, s51, 0
	s_add_u32 s52, s52, 0x80
	s_addc_u32 s53, s53, 0
	s_waitcnt vmcnt(0)
	ds_read_b128 v[124:127], v246
	ds_read_b128 v[128:131], v246 offset:2048
	ds_read_b128 v[132:135], v246 offset:4096
	ds_read_b128 v[136:139], v246 offset:6144
	ds_read_b128 v[200:203], v246 offset:8192
	ds_read_b128 v[204:207], v246 offset:10240
	ds_read_b128 v[208:211], v246 offset:12288
	ds_read_b128 v[212:215], v246 offset:14336
	ds_read_b128 v[140:143], v247
	ds_read_b128 v[144:147], v247 offset:2048
	ds_read_b128 v[148:151], v247 offset:4096
	ds_read_b128 v[152:155], v247 offset:6144
	ds_read_b128 v[216:219], v247 offset:8192
	ds_read_b128 v[220:223], v247 offset:10240
	ds_read_b128 v[224:227], v247 offset:12288
	ds_read_b128 v[228:231], v247 offset:14336
	s_waitcnt lgkmcnt(0)
	s_add_u32 m0, s54, 0x0
	s_nop 0
	global_load_lds_dwordx4 v232, s[50:51]
	s_add_u32 m0, s54, 0x400
	s_nop 0
	global_load_lds_dwordx4 v233, s[50:51]
	s_add_u32 m0, s54, 0x800
	s_nop 0
	global_load_lds_dwordx4 v234, s[50:51]
	s_add_u32 m0, s54, 0xc00
	s_nop 0
	global_load_lds_dwordx4 v235, s[50:51]
	s_add_u32 m0, s54, 0x1000
	s_nop 0
	global_load_lds_dwordx4 v236, s[50:51]
	s_add_u32 m0, s54, 0x1400
	s_nop 0
	global_load_lds_dwordx4 v237, s[50:51]
	s_add_u32 m0, s54, 0x1800
	s_nop 0
	global_load_lds_dwordx4 v238, s[50:51]
	s_add_u32 m0, s54, 0x1c00
	s_nop 0
	global_load_lds_dwordx4 v239, s[50:51]
	s_add_u32 m0, s54, 0x2000
	s_nop 0
	global_load_lds_dwordx4 v232, s[52:53]
	s_add_u32 m0, s54, 0x2400
	s_nop 0
	global_load_lds_dwordx4 v233, s[52:53]
	s_add_u32 m0, s54, 0x2800
	s_nop 0
	global_load_lds_dwordx4 v234, s[52:53]
	s_add_u32 m0, s54, 0x2c00
	s_nop 0
	global_load_lds_dwordx4 v235, s[52:53]
	s_add_u32 m0, s54, 0x3000
	s_nop 0
	global_load_lds_dwordx4 v236, s[52:53]
	s_add_u32 m0, s54, 0x3400
	s_nop 0
	global_load_lds_dwordx4 v237, s[52:53]
	s_add_u32 m0, s54, 0x3800
	s_nop 0
	global_load_lds_dwordx4 v238, s[52:53]
	s_add_u32 m0, s54, 0x3c00
	s_nop 0
	global_load_lds_dwordx4 v239, s[52:53]
	s_add_u32 s50, s50, 0x80
	s_addc_u32 s51, s51, 0
	s_add_u32 s52, s52, 0x80
	s_addc_u32 s53, s53, 0
	v_mfma_f32_16x16x32_bf16 v[60:63], v[124:127], v[200:203], v[60:63]
	v_mfma_f32_16x16x32_bf16 v[52:55], v[124:127], v[204:207], v[52:55]
	v_mfma_f32_16x16x32_bf16 v[48:51], v[124:127], v[208:211], v[48:51]
	v_mfma_f32_16x16x32_bf16 v[44:47], v[124:127], v[212:215], v[44:47]
	v_mfma_f32_16x16x32_bf16 v[40:43], v[128:131], v[200:203], v[40:43]
	v_mfma_f32_16x16x32_bf16 v[36:39], v[128:131], v[204:207], v[36:39]
	v_mfma_f32_16x16x32_bf16 v[20:23], v[128:131], v[208:211], v[20:23]
	v_mfma_f32_16x16x32_bf16 v[12:15], v[128:131], v[212:215], v[12:15]
	v_mfma_f32_16x16x32_bf16 v[16:19], v[132:135], v[200:203], v[16:19]
	v_mfma_f32_16x16x32_bf16 v[24:27], v[132:135], v[204:207], v[24:27]
	v_mfma_f32_16x16x32_bf16 v[28:31], v[132:135], v[208:211], v[28:31]
	v_mfma_f32_16x16x32_bf16 v[32:35], v[132:135], v[212:215], v[32:35]
	v_mfma_f32_16x16x32_bf16 v[0:3], v[136:139], v[200:203], v[0:3]
	v_mfma_f32_16x16x32_bf16 v[4:7], v[136:139], v[204:207], v[4:7]
	v_mfma_f32_16x16x32_bf16 v[8:11], v[136:139], v[208:211], v[8:11]
	v_mfma_f32_16x16x32_bf16 v[56:59], v[136:139], v[212:215], v[56:59]
	v_mfma_f32_16x16x32_bf16 v[60:63], v[140:143], v[216:219], v[60:63]
	v_mfma_f32_16x16x32_bf16 v[52:55], v[140:143], v[220:223], v[52:55]
	v_mfma_f32_16x16x32_bf16 v[48:51], v[140:143], v[224:227], v[48:51]
	v_mfma_f32_16x16x32_bf16 v[44:47], v[140:143], v[228:231], v[44:47]
	v_mfma_f32_16x16x32_bf16 v[40:43], v[144:147], v[216:219], v[40:43]
	v_mfma_f32_16x16x32_bf16 v[36:39], v[144:147], v[220:223], v[36:39]
	v_mfma_f32_16x16x32_bf16 v[20:23], v[144:147], v[224:227], v[20:23]
	v_mfma_f32_16x16x32_bf16 v[12:15], v[144:147], v[228:231], v[12:15]
	v_mfma_f32_16x16x32_bf16 v[16:19], v[148:151], v[216:219], v[16:19]
	v_mfma_f32_16x16x32_bf16 v[24:27], v[148:151], v[220:223], v[24:27]
	v_mfma_f32_16x16x32_bf16 v[28:31], v[148:151], v[224:227], v[28:31]
	v_mfma_f32_16x16x32_bf16 v[32:35], v[148:151], v[228:231], v[32:35]
	v_mfma_f32_16x16x32_bf16 v[0:3], v[152:155], v[216:219], v[0:3]
	v_mfma_f32_16x16x32_bf16 v[4:7], v[152:155], v[220:223], v[4:7]
	v_mfma_f32_16x16x32_bf16 v[8:11], v[152:155], v[224:227], v[8:11]
	v_mfma_f32_16x16x32_bf16 v[56:59], v[152:155], v[228:231], v[56:59]
	s_waitcnt vmcnt(0)
; template <int NH>
; __device__ void gemm_sample_rows(const Params& p, const u16* __restrict__ A, const u16* __restrict__ Bt,
;                                  const float* __restrict__ resid, float* __restrict__ outf, unsigned char* smem, const int rep) {
;     ...
; #pragma unroll 2
;     for (int ks = 0; ks < 8; ++ks) {
;       bf16x8 af[4], bfr[4];
; #pragma unroll
;       for (int mf = 0; mf < 4; ++mf) af[mf] = *(const bf16x8*)(ap + (size_t)(mf * 16) * K + ks * 32);
; #pragma unroll
;       for (int nf = 0; nf < 4; ++nf) bfr[nf] = *(const bf16x8*)(bp + (size_t)(nf * 16) * K + ks * 32);
; #pragma unroll
;       for (int mf = 0; mf < 4; ++mf)
; #pragma unroll
;         for (int nf = 0; nf < 4; ++nf)
;           acc[mf][nf] = __builtin_amdgcn_mfma_f32_16x16x32_bf16(af[mf], bfr[nf], acc[mf][nf], 0, 0, 0);
;     }
	ds_read_b128 v[124:127], v246
	ds_read_b128 v[128:131], v246 offset:2048
	ds_read_b128 v[132:135], v246 offset:4096
	ds_read_b128 v[136:139], v246 offset:6144
	ds_read_b128 v[200:203], v246 offset:8192
	ds_read_b128 v[204:207], v246 offset:10240
	ds_read_b128 v[208:211], v246 offset:12288
	ds_read_b128 v[212:215], v246 offset:14336
	ds_read_b128 v[140:143], v247
	ds_read_b128 v[144:147], v247 offset:2048
	ds_read_b128 v[148:151], v247 offset:4096
	ds_read_b128 v[152:155], v247 offset:6144
	ds_read_b128 v[216:219], v247 offset:8192
	ds_read_b128 v[220:223], v247 offset:10240
	ds_read_b128 v[224:227], v247 offset:12288
	ds_read_b128 v[228:231], v247 offset:14336
	s_waitcnt lgkmcnt(0)
	s_add_u32 m0, s54, 0x0
	s_nop 0
	global_load_lds_dwordx4 v232, s[50:51]
	s_add_u32 m0, s54, 0x400
	s_nop 0
	global_load_lds_dwordx4 v233, s[50:51]
	s_add_u32 m0, s54, 0x800
	s_nop 0
	global_load_lds_dwordx4 v234, s[50:51]
	s_add_u32 m0, s54, 0xc00
	s_nop 0
	global_load_lds_dwordx4 v235, s[50:51]
	s_add_u32 m0, s54, 0x1000
	s_nop 0
	global_load_lds_dwordx4 v236, s[50:51]
	s_add_u32 m0, s54, 0x1400
	s_nop 0
	global_load_lds_dwordx4 v237, s[50:51]
	s_add_u32 m0, s54, 0x1800
	s_nop 0
	global_load_lds_dwordx4 v238, s[50:51]
	s_add_u32 m0, s54, 0x1c00
	s_nop 0
	global_load_lds_dwordx4 v239, s[50:51]
	s_add_u32 m0, s54, 0x2000
	s_nop 0
	global_load_lds_dwordx4 v232, s[52:53]
	s_add_u32 m0, s54, 0x2400
	s_nop 0
	global_load_lds_dwordx4 v233, s[52:53]
	s_add_u32 m0, s54, 0x2800
	s_nop 0
	global_load_lds_dwordx4 v234, s[52:53]
	s_add_u32 m0, s54, 0x2c00
	s_nop 0
	global_load_lds_dwordx4 v235, s[52:53]
	s_add_u32 m0, s54, 0x3000
	s_nop 0
	global_load_lds_dwordx4 v236, s[52:53]
	s_add_u32 m0, s54, 0x3400
	s_nop 0
	global_load_lds_dwordx4 v237, s[52:53]
	s_add_u32 m0, s54, 0x3800
	s_nop 0
	global_load_lds_dwordx4 v238, s[52:53]
	s_add_u32 m0, s54, 0x3c00
	s_nop 0
	global_load_lds_dwordx4 v239, s[52:53]
	s_add_u32 s50, s50, 0x80
	s_addc_u32 s51, s51, 0
	s_add_u32 s52, s52, 0x80
	s_addc_u32 s53, s53, 0
	v_mfma_f32_16x16x32_bf16 v[60:63], v[124:127], v[200:203], v[60:63]
	v_mfma_f32_16x16x32_bf16 v[52:55], v[124:127], v[204:207], v[52:55]
	v_mfma_f32_16x16x32_bf16 v[48:51], v[124:127], v[208:211], v[48:51]
	v_mfma_f32_16x16x32_bf16 v[44:47], v[124:127], v[212:215], v[44:47]
	v_mfma_f32_16x16x32_bf16 v[40:43], v[128:131], v[200:203], v[40:43]
	v_mfma_f32_16x16x32_bf16 v[36:39], v[128:131], v[204:207], v[36:39]
	v_mfma_f32_16x16x32_bf16 v[20:23], v[128:131], v[208:211], v[20:23]
	v_mfma_f32_16x16x32_bf16 v[12:15], v[128:131], v[212:215], v[12:15]
	v_mfma_f32_16x16x32_bf16 v[16:19], v[132:135], v[200:203], v[16:19]
	v_mfma_f32_16x16x32_bf16 v[24:27], v[132:135], v[204:207], v[24:27]
	v_mfma_f32_16x16x32_bf16 v[28:31], v[132:135], v[208:211], v[28:31]
	v_mfma_f32_16x16x32_bf16 v[32:35], v[132:135], v[212:215], v[32:35]
	v_mfma_f32_16x16x32_bf16 v[0:3], v[136:139], v[200:203], v[0:3]
	v_mfma_f32_16x16x32_bf16 v[4:7], v[136:139], v[204:207], v[4:7]
	v_mfma_f32_16x16x32_bf16 v[8:11], v[136:139], v[208:211], v[8:11]
	v_mfma_f32_16x16x32_bf16 v[56:59], v[136:139], v[212:215], v[56:59]
	v_mfma_f32_16x16x32_bf16 v[60:63], v[140:143], v[216:219], v[60:63]
	v_mfma_f32_16x16x32_bf16 v[52:55], v[140:143], v[220:223], v[52:55]
	v_mfma_f32_16x16x32_bf16 v[48:51], v[140:143], v[224:227], v[48:51]
	v_mfma_f32_16x16x32_bf16 v[44:47], v[140:143], v[228:231], v[44:47]
	v_mfma_f32_16x16x32_bf16 v[40:43], v[144:147], v[216:219], v[40:43]
	v_mfma_f32_16x16x32_bf16 v[36:39], v[144:147], v[220:223], v[36:39]
	v_mfma_f32_16x16x32_bf16 v[20:23], v[144:147], v[224:227], v[20:23]
	v_mfma_f32_16x16x32_bf16 v[12:15], v[144:147], v[228:231], v[12:15]
	v_mfma_f32_16x16x32_bf16 v[16:19], v[148:151], v[216:219], v[16:19]
	v_mfma_f32_16x16x32_bf16 v[24:27], v[148:151], v[220:223], v[24:27]
	v_mfma_f32_16x16x32_bf16 v[28:31], v[148:151], v[224:227], v[28:31]
	v_mfma_f32_16x16x32_bf16 v[32:35], v[148:151], v[228:231], v[32:35]
	v_mfma_f32_16x16x32_bf16 v[0:3], v[152:155], v[216:219], v[0:3]
	v_mfma_f32_16x16x32_bf16 v[4:7], v[152:155], v[220:223], v[4:7]
	v_mfma_f32_16x16x32_bf16 v[8:11], v[152:155], v[224:227], v[8:11]
	v_mfma_f32_16x16x32_bf16 v[56:59], v[152:155], v[228:231], v[56:59]
	s_waitcnt vmcnt(0)
	ds_read_b128 v[124:127], v246
	ds_read_b128 v[128:131], v246 offset:2048
	ds_read_b128 v[132:135], v246 offset:4096
	ds_read_b128 v[136:139], v246 offset:6144
	ds_read_b128 v[200:203], v246 offset:8192
	ds_read_b128 v[204:207], v246 offset:10240
	ds_read_b128 v[208:211], v246 offset:12288
	ds_read_b128 v[212:215], v246 offset:14336
	ds_read_b128 v[140:143], v247
	ds_read_b128 v[144:147], v247 offset:2048
	ds_read_b128 v[148:151], v247 offset:4096
	ds_read_b128 v[152:155], v247 offset:6144
	ds_read_b128 v[216:219], v247 offset:8192
	ds_read_b128 v[220:223], v247 offset:10240
	ds_read_b128 v[224:227], v247 offset:12288
	ds_read_b128 v[228:231], v247 offset:14336
	s_waitcnt lgkmcnt(0)
; template <int NH>
; __device__ void gemm_sample_rows(const Params& p, const u16* __restrict__ A, const u16* __restrict__ Bt,
;                                  const float* __restrict__ resid, float* __restrict__ outf, unsigned char* smem, const int rep) {
;     ...
; #pragma unroll 2
;     for (int ks = 0; ks < 8; ++ks) {
;       bf16x8 af[4], bfr[4];
; #pragma unroll
;       for (int mf = 0; mf < 4; ++mf) af[mf] = *(const bf16x8*)(ap + (size_t)(mf * 16) * K + ks * 32);
; #pragma unroll
;       for (int nf = 0; nf < 4; ++nf) bfr[nf] = *(const bf16x8*)(bp + (size_t)(nf * 16) * K + ks * 32);
; #pragma unroll
;       for (int mf = 0; mf < 4; ++mf)
; #pragma unroll
;         for (int nf = 0; nf < 4; ++nf)
;           acc[mf][nf] = __builtin_amdgcn_mfma_f32_16x16x32_bf16(af[mf], bfr[nf], acc[mf][nf], 0, 0, 0);
;     }
;     __syncthreads();
	s_add_u32 m0, s54, 0x0
	s_nop 0
	global_load_lds_dwordx4 v232, s[50:51]
	s_add_u32 m0, s54, 0x400
	s_nop 0
	global_load_lds_dwordx4 v233, s[50:51]
	s_add_u32 m0, s54, 0x800
	s_nop 0
	global_load_lds_dwordx4 v234, s[50:51]
	s_add_u32 m0, s54, 0xc00
	s_nop 0
	global_load_lds_dwordx4 v235, s[50:51]
	s_add_u32 m0, s54, 0x1000
	s_nop 0
	global_load_lds_dwordx4 v236, s[50:51]
	s_add_u32 m0, s54, 0x1400
	s_nop 0
	global_load_lds_dwordx4 v237, s[50:51]
	s_add_u32 m0, s54, 0x1800
	s_nop 0
	global_load_lds_dwordx4 v238, s[50:51]
	s_add_u32 m0, s54, 0x1c00
	s_nop 0
	global_load_lds_dwordx4 v239, s[50:51]
	s_add_u32 m0, s54, 0x2000
	s_nop 0
	global_load_lds_dwordx4 v232, s[52:53]
	s_add_u32 m0, s54, 0x2400
	s_nop 0
	global_load_lds_dwordx4 v233, s[52:53]
	s_add_u32 m0, s54, 0x2800
	s_nop 0
	global_load_lds_dwordx4 v234, s[52:53]
	s_add_u32 m0, s54, 0x2c00
	s_nop 0
	global_load_lds_dwordx4 v235, s[52:53]
	s_add_u32 m0, s54, 0x3000
	s_nop 0
	global_load_lds_dwordx4 v236, s[52:53]
	s_add_u32 m0, s54, 0x3400
	s_nop 0
	global_load_lds_dwordx4 v237, s[52:53]
	s_add_u32 m0, s54, 0x3800
	s_nop 0
	global_load_lds_dwordx4 v238, s[52:53]
	s_add_u32 m0, s54, 0x3c00
	s_nop 0
	global_load_lds_dwordx4 v239, s[52:53]
	s_add_u32 s50, s50, 0x80
	s_addc_u32 s51, s51, 0
	s_add_u32 s52, s52, 0x80
	s_addc_u32 s53, s53, 0
	v_mfma_f32_16x16x32_bf16 v[60:63], v[124:127], v[200:203], v[60:63]
	v_mfma_f32_16x16x32_bf16 v[52:55], v[124:127], v[204:207], v[52:55]
	v_mfma_f32_16x16x32_bf16 v[48:51], v[124:127], v[208:211], v[48:51]
	v_mfma_f32_16x16x32_bf16 v[44:47], v[124:127], v[212:215], v[44:47]
	v_mfma_f32_16x16x32_bf16 v[40:43], v[128:131], v[200:203], v[40:43]
	v_mfma_f32_16x16x32_bf16 v[36:39], v[128:131], v[204:207], v[36:39]
	v_mfma_f32_16x16x32_bf16 v[20:23], v[128:131], v[208:211], v[20:23]
	v_mfma_f32_16x16x32_bf16 v[12:15], v[128:131], v[212:215], v[12:15]
	v_mfma_f32_16x16x32_bf16 v[16:19], v[132:135], v[200:203], v[16:19]
	v_mfma_f32_16x16x32_bf16 v[24:27], v[132:135], v[204:207], v[24:27]
	v_mfma_f32_16x16x32_bf16 v[28:31], v[132:135], v[208:211], v[28:31]
	v_mfma_f32_16x16x32_bf16 v[32:35], v[132:135], v[212:215], v[32:35]
	v_mfma_f32_16x16x32_bf16 v[0:3], v[136:139], v[200:203], v[0:3]
	v_mfma_f32_16x16x32_bf16 v[4:7], v[136:139], v[204:207], v[4:7]
	v_mfma_f32_16x16x32_bf16 v[8:11], v[136:139], v[208:211], v[8:11]
	v_mfma_f32_16x16x32_bf16 v[56:59], v[136:139], v[212:215], v[56:59]
	v_mfma_f32_16x16x32_bf16 v[60:63], v[140:143], v[216:219], v[60:63]
	v_mfma_f32_16x16x32_bf16 v[52:55], v[140:143], v[220:223], v[52:55]
	v_mfma_f32_16x16x32_bf16 v[48:51], v[140:143], v[224:227], v[48:51]
	v_mfma_f32_16x16x32_bf16 v[44:47], v[140:143], v[228:231], v[44:47]
	v_mfma_f32_16x16x32_bf16 v[40:43], v[144:147], v[216:219], v[40:43]
	v_mfma_f32_16x16x32_bf16 v[36:39], v[144:147], v[220:223], v[36:39]
	v_mfma_f32_16x16x32_bf16 v[20:23], v[144:147], v[224:227], v[20:23]
	v_mfma_f32_16x16x32_bf16 v[12:15], v[144:147], v[228:231], v[12:15]
	v_mfma_f32_16x16x32_bf16 v[16:19], v[148:151], v[216:219], v[16:19]
	v_mfma_f32_16x16x32_bf16 v[24:27], v[148:151], v[220:223], v[24:27]
	v_mfma_f32_16x16x32_bf16 v[28:31], v[148:151], v[224:227], v[28:31]
	v_mfma_f32_16x16x32_bf16 v[32:35], v[148:151], v[228:231], v[32:35]
	v_mfma_f32_16x16x32_bf16 v[0:3], v[152:155], v[216:219], v[0:3]
	v_mfma_f32_16x16x32_bf16 v[4:7], v[152:155], v[220:223], v[4:7]
	v_mfma_f32_16x16x32_bf16 v[8:11], v[152:155], v[224:227], v[8:11]
	v_mfma_f32_16x16x32_bf16 v[56:59], v[152:155], v[228:231], v[56:59]
	s_waitcnt vmcnt(0)
	ds_read_b128 v[124:127], v246
	ds_read_b128 v[128:131], v246 offset:2048
	ds_read_b128 v[132:135], v246 offset:4096
	ds_read_b128 v[136:139], v246 offset:6144
	ds_read_b128 v[200:203], v246 offset:8192
	ds_read_b128 v[204:207], v246 offset:10240
	ds_read_b128 v[208:211], v246 offset:12288
	ds_read_b128 v[212:215], v246 offset:14336
	ds_read_b128 v[140:143], v247
	ds_read_b128 v[144:147], v247 offset:2048
	ds_read_b128 v[148:151], v247 offset:4096
	ds_read_b128 v[152:155], v247 offset:6144
	ds_read_b128 v[216:219], v247 offset:8192
	ds_read_b128 v[220:223], v247 offset:10240
	ds_read_b128 v[224:227], v247 offset:12288
	ds_read_b128 v[228:231], v247 offset:14336
	s_waitcnt lgkmcnt(0)
	v_mfma_f32_16x16x32_bf16 v[60:63], v[124:127], v[200:203], v[60:63]
	v_mfma_f32_16x16x32_bf16 v[52:55], v[124:127], v[204:207], v[52:55]
	v_mfma_f32_16x16x32_bf16 v[48:51], v[124:127], v[208:211], v[48:51]
	v_mfma_f32_16x16x32_bf16 v[44:47], v[124:127], v[212:215], v[44:47]
	v_mfma_f32_16x16x32_bf16 v[40:43], v[128:131], v[200:203], v[40:43]
	v_mfma_f32_16x16x32_bf16 v[36:39], v[128:131], v[204:207], v[36:39]
	v_mfma_f32_16x16x32_bf16 v[20:23], v[128:131], v[208:211], v[20:23]
	v_mfma_f32_16x16x32_bf16 v[12:15], v[128:131], v[212:215], v[12:15]
	v_mfma_f32_16x16x32_bf16 v[16:19], v[132:135], v[200:203], v[16:19]
	v_mfma_f32_16x16x32_bf16 v[24:27], v[132:135], v[204:207], v[24:27]
	v_mfma_f32_16x16x32_bf16 v[28:31], v[132:135], v[208:211], v[28:31]
	v_mfma_f32_16x16x32_bf16 v[32:35], v[132:135], v[212:215], v[32:35]
	v_mfma_f32_16x16x32_bf16 v[0:3], v[136:139], v[200:203], v[0:3]
	v_mfma_f32_16x16x32_bf16 v[4:7], v[136:139], v[204:207], v[4:7]
	v_mfma_f32_16x16x32_bf16 v[8:11], v[136:139], v[208:211], v[8:11]
	v_mfma_f32_16x16x32_bf16 v[56:59], v[136:139], v[212:215], v[56:59]
	v_mfma_f32_16x16x32_bf16 v[60:63], v[140:143], v[216:219], v[60:63]
	v_mfma_f32_16x16x32_bf16 v[52:55], v[140:143], v[220:223], v[52:55]
	v_mfma_f32_16x16x32_bf16 v[48:51], v[140:143], v[224:227], v[48:51]
	v_mfma_f32_16x16x32_bf16 v[44:47], v[140:143], v[228:231], v[44:47]
	v_mfma_f32_16x16x32_bf16 v[40:43], v[144:147], v[216:219], v[40:43]
	v_mfma_f32_16x16x32_bf16 v[36:39], v[144:147], v[220:223], v[36:39]
	v_mfma_f32_16x16x32_bf16 v[20:23], v[144:147], v[224:227], v[20:23]
	v_mfma_f32_16x16x32_bf16 v[12:15], v[144:147], v[228:231], v[12:15]
	v_mfma_f32_16x16x32_bf16 v[16:19], v[148:151], v[216:219], v[16:19]
	v_mfma_f32_16x16x32_bf16 v[24:27], v[148:151], v[220:223], v[24:27]
	v_mfma_f32_16x16x32_bf16 v[28:31], v[148:151], v[224:227], v[28:31]
	v_mfma_f32_16x16x32_bf16 v[32:35], v[148:151], v[228:231], v[32:35]
	v_mfma_f32_16x16x32_bf16 v[0:3], v[152:155], v[216:219], v[0:3]
	v_mfma_f32_16x16x32_bf16 v[4:7], v[152:155], v[220:223], v[4:7]
	v_mfma_f32_16x16x32_bf16 v[8:11], v[152:155], v[224:227], v[8:11]
	v_mfma_f32_16x16x32_bf16 v[56:59], v[152:155], v[228:231], v[56:59]
	s_movk_i32 s4, 0x200
	s_mov_b32 s5, 0
	s_cmpk_eq_i32 s4, 0x200
	s_waitcnt lgkmcnt(0)
	s_barrier
; template <int NH>
; __device__ void gemm_sample_rows(const Params& p, const u16* __restrict__ A, const u16* __restrict__ Bt,
;                                  const float* __restrict__ resid, float* __restrict__ outf, unsigned char* smem, const int rep) {
;     ...
;     __syncthreads();
;     {
;       const int h = (w * 256) / (K / NH);
; #pragma unroll
;       for (int mf = 0; mf < 4; ++mf)
; #pragma unroll
;         for (int r = 0; r < 4; ++r) {
;           const int row = mf * 16 + 4 * g + r;
;           const float sc = rstdS[row * NH + h];
; #pragma unroll
;           for (int nf = 0; nf < 4; ++nf) red[(w * 64 + row) * RS + nf * 16 + l15] = acc[mf][nf][r] * sc;
;         }
;     }
;     __syncthreads();
	ds_read_b32 v66, v90
	s_add_i32 s15, s15, s16
	s_add_i32 s17, s17, s18
	s_waitcnt lgkmcnt(0)
	v_mul_f32_e32 v60, v60, v66
	v_mul_f32_e32 v52, v52, v66
	v_mul_f32_e32 v48, v48, v66
	v_mul_f32_e32 v44, v44, v66
	ds_write2_b32 v91, v60, v52 offset1:16
	ds_write2_b32 v91, v48, v44 offset0:32 offset1:48
	ds_read_b32 v44, v92
	s_waitcnt lgkmcnt(0)
	v_mul_f32_e32 v48, v61, v44
	v_mul_f32_e32 v52, v53, v44
	ds_write2_b32 v93, v48, v52 offset1:16
	v_mul_f32_e32 v48, v49, v44
	v_mul_f32_e32 v44, v45, v44
	ds_write2_b32 v93, v48, v44 offset0:32 offset1:48
	ds_read_b32 v44, v94
	s_waitcnt lgkmcnt(0)
	v_mul_f32_e32 v45, v62, v44
	v_mul_f32_e32 v48, v54, v44
	ds_write2_b32 v95, v45, v48 offset1:16
	v_mul_f32_e32 v45, v50, v44
	v_mul_f32_e32 v44, v46, v44
	ds_write2_b32 v95, v45, v44 offset0:32 offset1:48
	ds_read_b32 v44, v96
	s_waitcnt lgkmcnt(0)
	v_mul_f32_e32 v45, v63, v44
	v_mul_f32_e32 v46, v55, v44
	ds_write2_b32 v97, v45, v46 offset1:16
	v_mul_f32_e32 v45, v51, v44
	v_mul_f32_e32 v44, v47, v44
	ds_write2_b32 v97, v45, v44 offset0:32 offset1:48
	ds_read_b32 v44, v98
	s_waitcnt lgkmcnt(0)
	v_mul_f32_e32 v40, v40, v44
	v_mul_f32_e32 v36, v36, v44
	v_mul_f32_e32 v20, v20, v44
	v_mul_f32_e32 v12, v12, v44
	ds_write2_b32 v99, v40, v36 offset1:16
	ds_write2_b32 v99, v20, v12 offset0:32 offset1:48
	ds_read_b32 v12, v100
	v_add_u32_e32 v40, 0xc318, v70
	s_waitcnt lgkmcnt(0)
	v_mul_f32_e32 v20, v41, v12
	v_mul_f32_e32 v36, v37, v12
	ds_write2_b32 v101, v20, v36 offset1:16
	v_mul_f32_e32 v20, v21, v12
	v_mul_f32_e32 v12, v13, v12
	ds_write2_b32 v101, v20, v12 offset0:32 offset1:48
	ds_read_b32 v12, v102
	v_add_u32_e32 v36, 0x4118, v70
	s_waitcnt lgkmcnt(0)
	v_mul_f32_e32 v13, v42, v12
	v_mul_f32_e32 v20, v38, v12
	ds_write2_b32 v103, v13, v20 offset1:16
	v_mul_f32_e32 v13, v22, v12
	v_mul_f32_e32 v12, v14, v12
	ds_write2_b32 v103, v13, v12 offset0:32 offset1:48
	ds_read_b32 v12, v104
	v_add_u32_e32 v20, 0xc308, v70
	v_add_u32_e32 v22, 0x4110, v70
	v_add_u32_e32 v38, 0x8218, v70
	s_waitcnt lgkmcnt(0)
	v_mul_f32_e32 v13, v43, v12
	v_mul_f32_e32 v14, v39, v12
	ds_write2_b32 v105, v13, v14 offset1:16
	v_mul_f32_e32 v13, v23, v12
	v_mul_f32_e32 v12, v15, v12
	ds_write2_b32 v105, v13, v12 offset0:32 offset1:48
	ds_read_b32 v12, v106
	s_waitcnt lgkmcnt(0)
	v_mul_f32_e32 v13, v16, v12
	v_mul_f32_e32 v14, v24, v12
	ds_write2_b32 v107, v13, v14 offset1:16
	v_mul_f32_e32 v13, v28, v12
	v_mul_f32_e32 v12, v32, v12
	ds_write2_b32 v107, v13, v12 offset0:32 offset1:48
	ds_read_b32 v12, v108
	v_add_u32_e32 v16, 0x4108, v70
	v_add_u32_e32 v24, 0x8210, v70
	s_waitcnt lgkmcnt(0)
	v_mul_f32_e32 v13, v17, v12
	v_mul_f32_e32 v14, v25, v12
	ds_write2_b32 v109, v13, v14 offset1:16
	v_mul_f32_e32 v13, v29, v12
	v_mul_f32_e32 v12, v33, v12
	ds_write2_b32 v109, v13, v12 offset0:32 offset1:48
	ds_read_b32 v12, v110
	s_waitcnt lgkmcnt(0)
	v_mul_f32_e32 v13, v18, v12
	v_mul_f32_e32 v14, v26, v12
	ds_write2_b32 v111, v13, v14 offset1:16
	v_mul_f32_e32 v13, v30, v12
	v_mul_f32_e32 v12, v34, v12
	ds_write2_b32 v111, v13, v12 offset0:32 offset1:48
	ds_read_b32 v12, v112
	v_add_u32_e32 v18, 0x8208, v70
	v_add_u32_e32 v34, 0xc310, v70
	s_waitcnt lgkmcnt(0)
	v_mul_f32_e32 v13, v19, v12
	v_mul_f32_e32 v14, v27, v12
	ds_write2_b32 v113, v13, v14 offset1:16
	v_mul_f32_e32 v13, v31, v12
	v_mul_f32_e32 v12, v35, v12
	ds_write2_b32 v113, v13, v12 offset0:32 offset1:48
	ds_read_b32 v12, v114
	v_add_u32_e32 v14, 0xc300, v70
	s_waitcnt lgkmcnt(0)
	v_mul_f32_e32 v0, v0, v12
	v_mul_f32_e32 v4, v4, v12
	ds_write2_b32 v115, v0, v4 offset1:16
	v_mul_f32_e32 v0, v8, v12
	v_mul_f32_e32 v4, v56, v12
	ds_write2_b32 v115, v0, v4 offset0:32 offset1:48
	ds_read_b32 v0, v116
	v_add_u32_e32 v12, 0x8200, v70
	s_waitcnt lgkmcnt(0)
	v_mul_f32_e32 v1, v1, v0
	v_mul_f32_e32 v4, v5, v0
	ds_write2_b32 v117, v1, v4 offset1:16
	v_mul_f32_e32 v1, v9, v0
	v_mul_f32_e32 v0, v57, v0
	ds_write2_b32 v117, v1, v0 offset0:32 offset1:48
	ds_read_b32 v0, v118
	s_waitcnt lgkmcnt(0)
	v_mul_f32_e32 v1, v2, v0
	v_mul_f32_e32 v2, v6, v0
	ds_write2_b32 v119, v1, v2 offset1:16
	v_mul_f32_e32 v1, v10, v0
	v_mul_f32_e32 v0, v58, v0
	ds_write2_b32 v119, v1, v0 offset0:32 offset1:48
	ds_read_b32 v0, v120
	v_add_u32_e32 v10, 0x4100, v70
	s_waitcnt lgkmcnt(0)
	v_mul_f32_e32 v1, v3, v0
	v_mul_f32_e32 v2, v7, v0
	ds_write2_b32 v121, v1, v2 offset1:16
	v_mul_f32_e32 v1, v11, v0
	v_mul_f32_e32 v0, v59, v0
	ds_write2_b32 v121, v1, v0 offset0:32 offset1:48
	v_add_u32_e32 v0, s0, v197
	v_ashrrev_i32_e32 v1, 31, v0
	v_lshlrev_b64 v[0:1], 12, v[0:1]
	s_lshl_b32 s0, s29, 8
	v_lshl_add_u64 v[0:1], s[10:11], 0, v[0:1]
	s_and_b32 s0, s0, 0xf00
	v_lshl_add_u64 v[0:1], v[0:1], 0, s[0:1]
	v_lshl_add_u64 v[8:9], v[0:1], 0, v[180:181]
	s_waitcnt lgkmcnt(0)
	s_barrier
; template <int NH>
; __device__ void gemm_sample_rows(const Params& p, const u16* __restrict__ A, const u16* __restrict__ Bt,
;                                  const float* __restrict__ resid, float* __restrict__ outf, unsigned char* smem, const int rep) {
;     ...
;     {
;       const int row = tid >> 3, c0 = (tid & 7) * 8;
;       float o[8];
;       const size_t gidx = (size_t)(m0 + row) * 1024 + n0 + c0;
;       const float* rp = resid ? resid + gidx : p.x_sample + (size_t)(m0 - NPROMPT + row) * 1024 + n0 + c0;
;       const float4 r0 = *(const float4*)rp, r1 = *(const float4*)(rp + 4);
;       o[0] = r0.x; o[1] = r0.y; o[2] = r0.z; o[3] = r0.w; o[4] = r1.x; o[5] = r1.y; o[6] = r1.z; o[7] = r1.w;
; #pragma unroll
;       for (int ww = 0; ww < 8; ++ww)
; #pragma unroll
;         for (int j = 0; j < 8; ++j) o[j] += red[(ww * 64 + row) * RS + c0 + j];
;       *(float4*)(outf + gidx) = make_float4(o[0], o[1], o[2], o[3]);
;       *(float4*)(outf + gidx + 4) = make_float4(o[4], o[5], o[6], o[7]);
;     }
;     __syncthreads();
	global_load_dwordx4 v[0:3], v[8:9], off
	global_load_dwordx4 v[4:7], v[8:9], off offset:16
	ds_read2_b32 v[10:11], v10 offset1:1
	ds_read2_b32 v[12:13], v12 offset1:1
	ds_read2_b32 v[14:15], v14 offset1:1
	ds_read2_b32 v[16:17], v16 offset1:1
	ds_read2_b32 v[18:19], v18 offset1:1
	ds_read2_b32 v[20:21], v20 offset1:1
	ds_read2_b32 v[22:23], v22 offset1:1
	ds_read2_b32 v[24:25], v24 offset1:1
	ds_read2_b32 v[26:27], v70 offset1:1
	ds_read2_b32 v[28:29], v70 offset0:2 offset1:3
	ds_read2_b32 v[30:31], v70 offset0:4 offset1:5
	ds_read2_b32 v[32:33], v70 offset0:6 offset1:7
	ds_read2_b32 v[34:35], v34 offset1:1
	ds_read2_b32 v[36:37], v36 offset1:1
	ds_read2_b32 v[38:39], v38 offset1:1
	ds_read2_b32 v[40:41], v40 offset1:1
	ds_read2_b32 v[42:43], v71 offset1:1
	ds_read2_b32 v[44:45], v72 offset1:1
	ds_read2_b32 v[46:47], v73 offset1:1
	ds_read2_b32 v[48:49], v74 offset1:1
	ds_read2_b32 v[50:51], v75 offset1:1
	ds_read2_b32 v[52:53], v76 offset1:1
	ds_read2_b32 v[54:55], v77 offset1:1
	ds_read2_b32 v[56:57], v78 offset1:1
	ds_read2_b32 v[58:59], v79 offset1:1
	ds_read2_b32 v[60:61], v80 offset1:1
	ds_read2_b32 v[62:63], v81 offset1:1
	ds_read2_b32 v[66:67], v82 offset1:1
	ds_read2_b32 v[68:69], v83 offset1:1
	ds_read2_b32 v[124:125], v84 offset1:1
	ds_read2_b32 v[126:127], v85 offset1:1
	ds_read2_b32 v[128:129], v86 offset1:1
	v_add_u32_e32 v8, s30, v197
	v_ashrrev_i32_e32 v9, 31, v8
	v_lshlrev_b64 v[8:9], 12, v[8:9]
	v_lshl_add_u64 v[8:9], s[6:7], 0, v[8:9]
	v_lshl_add_u64 v[8:9], v[8:9], 0, s[0:1]
	v_lshl_add_u64 v[8:9], v[8:9], 0, v[180:181]
	s_add_i32 s29, s29, s96
	s_cmp_ge_i32 s29, s14
	s_waitcnt vmcnt(1) lgkmcnt(14)
	v_pk_add_f32 v[0:1], v[0:1], v[26:27]
	v_pk_add_f32 v[2:3], v[2:3], v[28:29]
	v_pk_add_f32 v[0:1], v[0:1], v[10:11]
	v_pk_add_f32 v[2:3], v[2:3], v[16:17]
	v_pk_add_f32 v[0:1], v[0:1], v[12:13]
	v_pk_add_f32 v[2:3], v[2:3], v[18:19]
	v_pk_add_f32 v[0:1], v[0:1], v[14:15]
	v_pk_add_f32 v[2:3], v[2:3], v[20:21]
	v_pk_add_f32 v[0:1], v[0:1], v[42:43]
	v_pk_add_f32 v[2:3], v[2:3], v[44:45]
	s_waitcnt lgkmcnt(11)
	v_pk_add_f32 v[0:1], v[0:1], v[50:51]
	s_waitcnt lgkmcnt(10)
	v_pk_add_f32 v[2:3], v[2:3], v[52:53]
	s_waitcnt lgkmcnt(7)
	v_pk_add_f32 v[0:1], v[0:1], v[58:59]
	s_waitcnt lgkmcnt(6)
	v_pk_add_f32 v[2:3], v[2:3], v[60:61]
	s_waitcnt lgkmcnt(3)
	v_pk_add_f32 v[0:1], v[0:1], v[68:69]
	s_waitcnt lgkmcnt(2)
	v_pk_add_f32 v[2:3], v[2:3], v[124:125]
	s_waitcnt vmcnt(0)
	v_pk_add_f32 v[4:5], v[4:5], v[30:31]
	global_store_dwordx4 v[8:9], v[0:3], off
	v_pk_add_f32 v[4:5], v[4:5], v[22:23]
	s_nop 0
	v_pk_add_f32 v[2:3], v[6:7], v[32:33]
	v_pk_add_f32 v[4:5], v[4:5], v[24:25]
	v_pk_add_f32 v[2:3], v[2:3], v[36:37]
	v_pk_add_f32 v[4:5], v[4:5], v[34:35]
	v_pk_add_f32 v[2:3], v[2:3], v[38:39]
	v_pk_add_f32 v[4:5], v[4:5], v[46:47]
	v_pk_add_f32 v[2:3], v[2:3], v[40:41]
	v_pk_add_f32 v[0:1], v[4:5], v[54:55]
	v_pk_add_f32 v[2:3], v[2:3], v[48:49]
	v_pk_add_f32 v[0:1], v[0:1], v[62:63]
	v_pk_add_f32 v[2:3], v[2:3], v[56:57]
	s_waitcnt lgkmcnt(1)
	v_pk_add_f32 v[0:1], v[0:1], v[126:127]
	v_pk_add_f32 v[2:3], v[2:3], v[66:67]
	s_waitcnt lgkmcnt(0)
	v_pk_add_f32 v[2:3], v[2:3], v[128:129]
	global_store_dwordx4 v[8:9], v[0:3], off offset:16
	s_barrier
	s_cbranch_scc0 .LBB0_726

; template <int NH>
; __device__ void gemm_sample_rows(const Params& p, const u16* __restrict__ A, const u16* __restrict__ Bt,
;                                  const float* __restrict__ resid, float* __restrict__ outf, unsigned char* smem, const int rep) {
;     ...
;     const u16* ap = A + (size_t)(m0 + l15) * K + w * 256 + 8 * g;
;     const u16* bp = Bt + (size_t)(n0 + l15) * K + w * 256 + 8 * g;
; #pragma unroll 2
;     for (int ks = 0; ks < 8; ++ks) {
;       bf16x8 af[4], bfr[4];
; #pragma unroll
;       for (int mf = 0; mf < 4; ++mf) af[mf] = *(const bf16x8*)(ap + (size_t)(mf * 16) * K + ks * 32);
; #pragma unroll
;       for (int nf = 0; nf < 4; ++nf) bfr[nf] = *(const bf16x8*)(bp + (size_t)(nf * 16) * K + ks * 32);
; #pragma unroll
;       for (int mf = 0; mf < 4; ++mf)
; #pragma unroll
;         for (int nf = 0; nf < 4; ++nf)
;           acc[mf][nf] = __builtin_amdgcn_mfma_f32_16x16x32_bf16(af[mf], bfr[nf], acc[mf][nf], 0, 0, 0);
;     }
.LBB0_2035:
	v_readfirstlane_b32 s50, v68
	v_readfirstlane_b32 s51, v69
	s_add_u32 s50, s50, s18
	s_addc_u32 s51, s51, 0
	v_readfirstlane_b32 s52, v70
	v_readfirstlane_b32 s53, v71
	s_add_u32 s52, s52, s22
	s_addc_u32 s53, s53, 0
	v_readlane_b32 s54, v255, 6
	s_lshl_b32 s54, s54, 14
	v_mbcnt_lo_u32_b32 v240, -1, 0
	v_mbcnt_hi_u32_b32 v240, -1, v240
	v_lshrrev_b32_e32 v241, 3, v240
	v_lshlrev_b32_e32 v241, 12, v241
	v_and_b32_e32 v242, 7, v240
	v_lshrrev_b32_e32 v243, 4, v240
	v_xor_b32_e32 v244, v242, v243
	v_lshl_add_u32 v232, v244, 4, v241
	v_xor_b32_e32 v244, 4, v244
	v_lshl_add_u32 v233, v244, 4, v241
	v_add_u32_e32 v233, 0x8000, v233
	v_add_u32_e32 v234, 0x10000, v232
	v_add_u32_e32 v235, 0x10000, v233
	v_add_u32_e32 v236, 0x20000, v232
	v_add_u32_e32 v237, 0x20000, v233
	v_add_u32_e32 v238, 0x30000, v232
	v_add_u32_e32 v239, 0x30000, v233
	v_and_b32_e32 v245, 15, v240
	v_lshrrev_b32_e32 v246, 1, v245
	v_xor_b32_e32 v246, v243, v246
	v_lshlrev_b32_e32 v246, 4, v246
	v_lshl_add_u32 v246, v245, 7, v246
	v_add_u32_e32 v246, s54, v246
	v_xor_b32_e32 v247, 64, v246
	s_add_u32 m0, s54, 0x0
	s_nop 0
	global_load_lds_dwordx4 v232, s[50:51]
	s_add_u32 m0, s54, 0x400
	s_nop 0
	global_load_lds_dwordx4 v233, s[50:51]
	s_add_u32 m0, s54, 0x800
	s_nop 0
	global_load_lds_dwordx4 v234, s[50:51]
	s_add_u32 m0, s54, 0xc00
	s_nop 0
	global_load_lds_dwordx4 v235, s[50:51]
	s_add_u32 m0, s54, 0x1000
	s_nop 0
	global_load_lds_dwordx4 v236, s[50:51]
	s_add_u32 m0, s54, 0x1400
	s_nop 0
	global_load_lds_dwordx4 v237, s[50:51]
	s_add_u32 m0, s54, 0x1800
	s_nop 0
	global_load_lds_dwordx4 v238, s[50:51]
	s_add_u32 m0, s54, 0x1c00
	s_nop 0
	global_load_lds_dwordx4 v239, s[50:51]
	s_add_u32 m0, s54, 0x2000
	s_nop 0
	global_load_lds_dwordx4 v232, s[52:53]
	s_add_u32 m0, s54, 0x2400
	s_nop 0
	global_load_lds_dwordx4 v233, s[52:53]
	s_add_u32 m0, s54, 0x2800
	s_nop 0
	global_load_lds_dwordx4 v234, s[52:53]
	s_add_u32 m0, s54, 0x2c00
	s_nop 0
	global_load_lds_dwordx4 v235, s[52:53]
	s_add_u32 m0, s54, 0x3000
	s_nop 0
	global_load_lds_dwordx4 v236, s[52:53]
	s_add_u32 m0, s54, 0x3400
	s_nop 0
	global_load_lds_dwordx4 v237, s[52:53]
	s_add_u32 m0, s54, 0x3800
	s_nop 0
	global_load_lds_dwordx4 v238, s[52:53]
	s_add_u32 m0, s54, 0x3c00
	s_nop 0
	global_load_lds_dwordx4 v239, s[52:53]
	s_add_u32 s50, s50, 0x80
	s_addc_u32 s51, s51, 0
	s_add_u32 s52, s52, 0x80
	s_addc_u32 s53, s53, 0
	s_waitcnt vmcnt(0)
	ds_read_b128 v[124:127], v246
	ds_read_b128 v[128:131], v246 offset:2048
	ds_read_b128 v[132:135], v246 offset:4096
	ds_read_b128 v[136:139], v246 offset:6144
	ds_read_b128 v[200:203], v246 offset:8192
	ds_read_b128 v[204:207], v246 offset:10240
	ds_read_b128 v[208:211], v246 offset:12288
	ds_read_b128 v[212:215], v246 offset:14336
	ds_read_b128 v[140:143], v247
	ds_read_b128 v[144:147], v247 offset:2048
	ds_read_b128 v[148:151], v247 offset:4096
	ds_read_b128 v[152:155], v247 offset:6144
	ds_read_b128 v[216:219], v247 offset:8192
	ds_read_b128 v[220:223], v247 offset:10240
	ds_read_b128 v[224:227], v247 offset:12288
	ds_read_b128 v[228:231], v247 offset:14336
	s_waitcnt lgkmcnt(0)
	s_add_u32 m0, s54, 0x0
	s_nop 0
	global_load_lds_dwordx4 v232, s[50:51]
	s_add_u32 m0, s54, 0x400
	s_nop 0
	global_load_lds_dwordx4 v233, s[50:51]
	s_add_u32 m0, s54, 0x800
	s_nop 0
	global_load_lds_dwordx4 v234, s[50:51]
	s_add_u32 m0, s54, 0xc00
	s_nop 0
	global_load_lds_dwordx4 v235, s[50:51]
	s_add_u32 m0, s54, 0x1000
	s_nop 0
	global_load_lds_dwordx4 v236, s[50:51]
	s_add_u32 m0, s54, 0x1400
	s_nop 0
	global_load_lds_dwordx4 v237, s[50:51]
	s_add_u32 m0, s54, 0x1800
	s_nop 0
	global_load_lds_dwordx4 v238, s[50:51]
	s_add_u32 m0, s54, 0x1c00
	s_nop 0
	global_load_lds_dwordx4 v239, s[50:51]
	s_add_u32 m0, s54, 0x2000
	s_nop 0
	global_load_lds_dwordx4 v232, s[52:53]
	s_add_u32 m0, s54, 0x2400
	s_nop 0
	global_load_lds_dwordx4 v233, s[52:53]
	s_add_u32 m0, s54, 0x2800
	s_nop 0
	global_load_lds_dwordx4 v234, s[52:53]
	s_add_u32 m0, s54, 0x2c00
	s_nop 0
	global_load_lds_dwordx4 v235, s[52:53]
	s_add_u32 m0, s54, 0x3000
	s_nop 0
	global_load_lds_dwordx4 v236, s[52:53]
	s_add_u32 m0, s54, 0x3400
	s_nop 0
	global_load_lds_dwordx4 v237, s[52:53]
	s_add_u32 m0, s54, 0x3800
	s_nop 0
	global_load_lds_dwordx4 v238, s[52:53]
	s_add_u32 m0, s54, 0x3c00
	s_nop 0
	global_load_lds_dwordx4 v239, s[52:53]
	s_add_u32 s50, s50, 0x80
	s_addc_u32 s51, s51, 0
	s_add_u32 s52, s52, 0x80
	s_addc_u32 s53, s53, 0
	v_mfma_f32_16x16x32_bf16 v[60:63], v[124:127], v[200:203], v[60:63]
	v_mfma_f32_16x16x32_bf16 v[56:59], v[124:127], v[204:207], v[56:59]
	v_mfma_f32_16x16x32_bf16 v[48:51], v[124:127], v[208:211], v[48:51]
	v_mfma_f32_16x16x32_bf16 v[44:47], v[124:127], v[212:215], v[44:47]
	v_mfma_f32_16x16x32_bf16 v[40:43], v[128:131], v[200:203], v[40:43]
	v_mfma_f32_16x16x32_bf16 v[36:39], v[128:131], v[204:207], v[36:39]
	v_mfma_f32_16x16x32_bf16 v[20:23], v[128:131], v[208:211], v[20:23]
	v_mfma_f32_16x16x32_bf16 v[12:15], v[128:131], v[212:215], v[12:15]
	v_mfma_f32_16x16x32_bf16 v[16:19], v[132:135], v[200:203], v[16:19]
	v_mfma_f32_16x16x32_bf16 v[24:27], v[132:135], v[204:207], v[24:27]
	v_mfma_f32_16x16x32_bf16 v[28:31], v[132:135], v[208:211], v[28:31]
	v_mfma_f32_16x16x32_bf16 v[32:35], v[132:135], v[212:215], v[32:35]
	v_mfma_f32_16x16x32_bf16 v[0:3], v[136:139], v[200:203], v[0:3]
	v_mfma_f32_16x16x32_bf16 v[4:7], v[136:139], v[204:207], v[4:7]
	v_mfma_f32_16x16x32_bf16 v[8:11], v[136:139], v[208:211], v[8:11]
	v_mfma_f32_16x16x32_bf16 v[52:55], v[136:139], v[212:215], v[52:55]
	v_mfma_f32_16x16x32_bf16 v[60:63], v[140:143], v[216:219], v[60:63]
	v_mfma_f32_16x16x32_bf16 v[56:59], v[140:143], v[220:223], v[56:59]
	v_mfma_f32_16x16x32_bf16 v[48:51], v[140:143], v[224:227], v[48:51]
	v_mfma_f32_16x16x32_bf16 v[44:47], v[140:143], v[228:231], v[44:47]
	v_mfma_f32_16x16x32_bf16 v[40:43], v[144:147], v[216:219], v[40:43]
	v_mfma_f32_16x16x32_bf16 v[36:39], v[144:147], v[220:223], v[36:39]
	v_mfma_f32_16x16x32_bf16 v[20:23], v[144:147], v[224:227], v[20:23]
	v_mfma_f32_16x16x32_bf16 v[12:15], v[144:147], v[228:231], v[12:15]
	v_mfma_f32_16x16x32_bf16 v[16:19], v[148:151], v[216:219], v[16:19]
	v_mfma_f32_16x16x32_bf16 v[24:27], v[148:151], v[220:223], v[24:27]
	v_mfma_f32_16x16x32_bf16 v[28:31], v[148:151], v[224:227], v[28:31]
	v_mfma_f32_16x16x32_bf16 v[32:35], v[148:151], v[228:231], v[32:35]
	v_mfma_f32_16x16x32_bf16 v[0:3], v[152:155], v[216:219], v[0:3]
	v_mfma_f32_16x16x32_bf16 v[4:7], v[152:155], v[220:223], v[4:7]
	v_mfma_f32_16x16x32_bf16 v[8:11], v[152:155], v[224:227], v[8:11]
	v_mfma_f32_16x16x32_bf16 v[52:55], v[152:155], v[228:231], v[52:55]
	s_waitcnt vmcnt(0)
; template <int NH>
; __device__ void gemm_sample_rows(const Params& p, const u16* __restrict__ A, const u16* __restrict__ Bt,
;                                  const float* __restrict__ resid, float* __restrict__ outf, unsigned char* smem, const int rep) {
;     ...
;     for (int ks = 0; ks < 8; ++ks) {
;       bf16x8 af[4], bfr[4];
; #pragma unroll
;       for (int mf = 0; mf < 4; ++mf) af[mf] = *(const bf16x8*)(ap + (size_t)(mf * 16) * K + ks * 32);
; #pragma unroll
;       for (int nf = 0; nf < 4; ++nf) bfr[nf] = *(const bf16x8*)(bp + (size_t)(nf * 16) * K + ks * 32);
; #pragma unroll
;       for (int mf = 0; mf < 4; ++mf)
; #pragma unroll
;         for (int nf = 0; nf < 4; ++nf)
;           acc[mf][nf] = __builtin_amdgcn_mfma_f32_16x16x32_bf16(af[mf], bfr[nf], acc[mf][nf], 0, 0, 0);
;     }
	ds_read_b128 v[124:127], v246
	ds_read_b128 v[128:131], v246 offset:2048
	ds_read_b128 v[132:135], v246 offset:4096
	ds_read_b128 v[136:139], v246 offset:6144
	ds_read_b128 v[200:203], v246 offset:8192
	ds_read_b128 v[204:207], v246 offset:10240
	ds_read_b128 v[208:211], v246 offset:12288
	ds_read_b128 v[212:215], v246 offset:14336
	ds_read_b128 v[140:143], v247
	ds_read_b128 v[144:147], v247 offset:2048
	ds_read_b128 v[148:151], v247 offset:4096
	ds_read_b128 v[152:155], v247 offset:6144
	ds_read_b128 v[216:219], v247 offset:8192
	ds_read_b128 v[220:223], v247 offset:10240
	ds_read_b128 v[224:227], v247 offset:12288
	ds_read_b128 v[228:231], v247 offset:14336
	s_waitcnt lgkmcnt(0)
	s_add_u32 m0, s54, 0x0
	s_nop 0
	global_load_lds_dwordx4 v232, s[50:51]
	s_add_u32 m0, s54, 0x400
	s_nop 0
	global_load_lds_dwordx4 v233, s[50:51]
	s_add_u32 m0, s54, 0x800
	s_nop 0
	global_load_lds_dwordx4 v234, s[50:51]
	s_add_u32 m0, s54, 0xc00
	s_nop 0
	global_load_lds_dwordx4 v235, s[50:51]
	s_add_u32 m0, s54, 0x1000
	s_nop 0
	global_load_lds_dwordx4 v236, s[50:51]
	s_add_u32 m0, s54, 0x1400
	s_nop 0
	global_load_lds_dwordx4 v237, s[50:51]
	s_add_u32 m0, s54, 0x1800
	s_nop 0
	global_load_lds_dwordx4 v238, s[50:51]
	s_add_u32 m0, s54, 0x1c00
	s_nop 0
	global_load_lds_dwordx4 v239, s[50:51]
	s_add_u32 m0, s54, 0x2000
	s_nop 0
	global_load_lds_dwordx4 v232, s[52:53]
	s_add_u32 m0, s54, 0x2400
	s_nop 0
	global_load_lds_dwordx4 v233, s[52:53]
	s_add_u32 m0, s54, 0x2800
	s_nop 0
	global_load_lds_dwordx4 v234, s[52:53]
	s_add_u32 m0, s54, 0x2c00
	s_nop 0
	global_load_lds_dwordx4 v235, s[52:53]
	s_add_u32 m0, s54, 0x3000
	s_nop 0
	global_load_lds_dwordx4 v236, s[52:53]
	s_add_u32 m0, s54, 0x3400
	s_nop 0
	global_load_lds_dwordx4 v237, s[52:53]
	s_add_u32 m0, s54, 0x3800
	s_nop 0
	global_load_lds_dwordx4 v238, s[52:53]
	s_add_u32 m0, s54, 0x3c00
	s_nop 0
	global_load_lds_dwordx4 v239, s[52:53]
	s_add_u32 s50, s50, 0x80
	s_addc_u32 s51, s51, 0
	s_add_u32 s52, s52, 0x80
	s_addc_u32 s53, s53, 0
	v_mfma_f32_16x16x32_bf16 v[60:63], v[124:127], v[200:203], v[60:63]
	v_mfma_f32_16x16x32_bf16 v[56:59], v[124:127], v[204:207], v[56:59]
	v_mfma_f32_16x16x32_bf16 v[48:51], v[124:127], v[208:211], v[48:51]
	v_mfma_f32_16x16x32_bf16 v[44:47], v[124:127], v[212:215], v[44:47]
	v_mfma_f32_16x16x32_bf16 v[40:43], v[128:131], v[200:203], v[40:43]
	v_mfma_f32_16x16x32_bf16 v[36:39], v[128:131], v[204:207], v[36:39]
	v_mfma_f32_16x16x32_bf16 v[20:23], v[128:131], v[208:211], v[20:23]
	v_mfma_f32_16x16x32_bf16 v[12:15], v[128:131], v[212:215], v[12:15]
	v_mfma_f32_16x16x32_bf16 v[16:19], v[132:135], v[200:203], v[16:19]
	v_mfma_f32_16x16x32_bf16 v[24:27], v[132:135], v[204:207], v[24:27]
	v_mfma_f32_16x16x32_bf16 v[28:31], v[132:135], v[208:211], v[28:31]
	v_mfma_f32_16x16x32_bf16 v[32:35], v[132:135], v[212:215], v[32:35]
	v_mfma_f32_16x16x32_bf16 v[0:3], v[136:139], v[200:203], v[0:3]
	v_mfma_f32_16x16x32_bf16 v[4:7], v[136:139], v[204:207], v[4:7]
	v_mfma_f32_16x16x32_bf16 v[8:11], v[136:139], v[208:211], v[8:11]
	v_mfma_f32_16x16x32_bf16 v[52:55], v[136:139], v[212:215], v[52:55]
	v_mfma_f32_16x16x32_bf16 v[60:63], v[140:143], v[216:219], v[60:63]
	v_mfma_f32_16x16x32_bf16 v[56:59], v[140:143], v[220:223], v[56:59]
	v_mfma_f32_16x16x32_bf16 v[48:51], v[140:143], v[224:227], v[48:51]
	v_mfma_f32_16x16x32_bf16 v[44:47], v[140:143], v[228:231], v[44:47]
	v_mfma_f32_16x16x32_bf16 v[40:43], v[144:147], v[216:219], v[40:43]
	v_mfma_f32_16x16x32_bf16 v[36:39], v[144:147], v[220:223], v[36:39]
	v_mfma_f32_16x16x32_bf16 v[20:23], v[144:147], v[224:227], v[20:23]
	v_mfma_f32_16x16x32_bf16 v[12:15], v[144:147], v[228:231], v[12:15]
	v_mfma_f32_16x16x32_bf16 v[16:19], v[148:151], v[216:219], v[16:19]
	v_mfma_f32_16x16x32_bf16 v[24:27], v[148:151], v[220:223], v[24:27]
	v_mfma_f32_16x16x32_bf16 v[28:31], v[148:151], v[224:227], v[28:31]
	v_mfma_f32_16x16x32_bf16 v[32:35], v[148:151], v[228:231], v[32:35]
	v_mfma_f32_16x16x32_bf16 v[0:3], v[152:155], v[216:219], v[0:3]
	v_mfma_f32_16x16x32_bf16 v[4:7], v[152:155], v[220:223], v[4:7]
	v_mfma_f32_16x16x32_bf16 v[8:11], v[152:155], v[224:227], v[8:11]
	v_mfma_f32_16x16x32_bf16 v[52:55], v[152:155], v[228:231], v[52:55]
	s_waitcnt vmcnt(0)
	ds_read_b128 v[124:127], v246
	ds_read_b128 v[128:131], v246 offset:2048
	ds_read_b128 v[132:135], v246 offset:4096
	ds_read_b128 v[136:139], v246 offset:6144
	ds_read_b128 v[200:203], v246 offset:8192
	ds_read_b128 v[204:207], v246 offset:10240
	ds_read_b128 v[208:211], v246 offset:12288
	ds_read_b128 v[212:215], v246 offset:14336
	ds_read_b128 v[140:143], v247
	ds_read_b128 v[144:147], v247 offset:2048
	ds_read_b128 v[148:151], v247 offset:4096
	ds_read_b128 v[152:155], v247 offset:6144
	ds_read_b128 v[216:219], v247 offset:8192
	ds_read_b128 v[220:223], v247 offset:10240
	ds_read_b128 v[224:227], v247 offset:12288
	ds_read_b128 v[228:231], v247 offset:14336
	s_waitcnt lgkmcnt(0)
; template <int NH>
; __device__ void gemm_sample_rows(const Params& p, const u16* __restrict__ A, const u16* __restrict__ Bt,
;                                  const float* __restrict__ resid, float* __restrict__ outf, unsigned char* smem, const int rep) {
;     ...
;     for (int ks = 0; ks < 8; ++ks) {
;       bf16x8 af[4], bfr[4];
; #pragma unroll
;       for (int mf = 0; mf < 4; ++mf) af[mf] = *(const bf16x8*)(ap + (size_t)(mf * 16) * K + ks * 32);
; #pragma unroll
;       for (int nf = 0; nf < 4; ++nf) bfr[nf] = *(const bf16x8*)(bp + (size_t)(nf * 16) * K + ks * 32);
; #pragma unroll
;       for (int mf = 0; mf < 4; ++mf)
; #pragma unroll
;         for (int nf = 0; nf < 4; ++nf)
;           acc[mf][nf] = __builtin_amdgcn_mfma_f32_16x16x32_bf16(af[mf], bfr[nf], acc[mf][nf], 0, 0, 0);
;     }
;     __syncthreads();
	s_add_u32 m0, s54, 0x0
	s_nop 0
	global_load_lds_dwordx4 v232, s[50:51]
	s_add_u32 m0, s54, 0x400
	s_nop 0
	global_load_lds_dwordx4 v233, s[50:51]
	s_add_u32 m0, s54, 0x800
	s_nop 0
	global_load_lds_dwordx4 v234, s[50:51]
	s_add_u32 m0, s54, 0xc00
	s_nop 0
	global_load_lds_dwordx4 v235, s[50:51]
	s_add_u32 m0, s54, 0x1000
	s_nop 0
	global_load_lds_dwordx4 v236, s[50:51]
	s_add_u32 m0, s54, 0x1400
	s_nop 0
	global_load_lds_dwordx4 v237, s[50:51]
	s_add_u32 m0, s54, 0x1800
	s_nop 0
	global_load_lds_dwordx4 v238, s[50:51]
	s_add_u32 m0, s54, 0x1c00
	s_nop 0
	global_load_lds_dwordx4 v239, s[50:51]
	s_add_u32 m0, s54, 0x2000
	s_nop 0
	global_load_lds_dwordx4 v232, s[52:53]
	s_add_u32 m0, s54, 0x2400
	s_nop 0
	global_load_lds_dwordx4 v233, s[52:53]
	s_add_u32 m0, s54, 0x2800
	s_nop 0
	global_load_lds_dwordx4 v234, s[52:53]
	s_add_u32 m0, s54, 0x2c00
	s_nop 0
	global_load_lds_dwordx4 v235, s[52:53]
	s_add_u32 m0, s54, 0x3000
	s_nop 0
	global_load_lds_dwordx4 v236, s[52:53]
	s_add_u32 m0, s54, 0x3400
	s_nop 0
	global_load_lds_dwordx4 v237, s[52:53]
	s_add_u32 m0, s54, 0x3800
	s_nop 0
	global_load_lds_dwordx4 v238, s[52:53]
	s_add_u32 m0, s54, 0x3c00
	s_nop 0
	global_load_lds_dwordx4 v239, s[52:53]
	s_add_u32 s50, s50, 0x80
	s_addc_u32 s51, s51, 0
	s_add_u32 s52, s52, 0x80
	s_addc_u32 s53, s53, 0
	v_mfma_f32_16x16x32_bf16 v[60:63], v[124:127], v[200:203], v[60:63]
	v_mfma_f32_16x16x32_bf16 v[56:59], v[124:127], v[204:207], v[56:59]
	v_mfma_f32_16x16x32_bf16 v[48:51], v[124:127], v[208:211], v[48:51]
	v_mfma_f32_16x16x32_bf16 v[44:47], v[124:127], v[212:215], v[44:47]
	v_mfma_f32_16x16x32_bf16 v[40:43], v[128:131], v[200:203], v[40:43]
	v_mfma_f32_16x16x32_bf16 v[36:39], v[128:131], v[204:207], v[36:39]
	v_mfma_f32_16x16x32_bf16 v[20:23], v[128:131], v[208:211], v[20:23]
	v_mfma_f32_16x16x32_bf16 v[12:15], v[128:131], v[212:215], v[12:15]
	v_mfma_f32_16x16x32_bf16 v[16:19], v[132:135], v[200:203], v[16:19]
	v_mfma_f32_16x16x32_bf16 v[24:27], v[132:135], v[204:207], v[24:27]
	v_mfma_f32_16x16x32_bf16 v[28:31], v[132:135], v[208:211], v[28:31]
	v_mfma_f32_16x16x32_bf16 v[32:35], v[132:135], v[212:215], v[32:35]
	v_mfma_f32_16x16x32_bf16 v[0:3], v[136:139], v[200:203], v[0:3]
	v_mfma_f32_16x16x32_bf16 v[4:7], v[136:139], v[204:207], v[4:7]
	v_mfma_f32_16x16x32_bf16 v[8:11], v[136:139], v[208:211], v[8:11]
	v_mfma_f32_16x16x32_bf16 v[52:55], v[136:139], v[212:215], v[52:55]
	v_mfma_f32_16x16x32_bf16 v[60:63], v[140:143], v[216:219], v[60:63]
	v_mfma_f32_16x16x32_bf16 v[56:59], v[140:143], v[220:223], v[56:59]
	v_mfma_f32_16x16x32_bf16 v[48:51], v[140:143], v[224:227], v[48:51]
	v_mfma_f32_16x16x32_bf16 v[44:47], v[140:143], v[228:231], v[44:47]
	v_mfma_f32_16x16x32_bf16 v[40:43], v[144:147], v[216:219], v[40:43]
	v_mfma_f32_16x16x32_bf16 v[36:39], v[144:147], v[220:223], v[36:39]
	v_mfma_f32_16x16x32_bf16 v[20:23], v[144:147], v[224:227], v[20:23]
	v_mfma_f32_16x16x32_bf16 v[12:15], v[144:147], v[228:231], v[12:15]
	v_mfma_f32_16x16x32_bf16 v[16:19], v[148:151], v[216:219], v[16:19]
	v_mfma_f32_16x16x32_bf16 v[24:27], v[148:151], v[220:223], v[24:27]
	v_mfma_f32_16x16x32_bf16 v[28:31], v[148:151], v[224:227], v[28:31]
	v_mfma_f32_16x16x32_bf16 v[32:35], v[148:151], v[228:231], v[32:35]
	v_mfma_f32_16x16x32_bf16 v[0:3], v[152:155], v[216:219], v[0:3]
	v_mfma_f32_16x16x32_bf16 v[4:7], v[152:155], v[220:223], v[4:7]
	v_mfma_f32_16x16x32_bf16 v[8:11], v[152:155], v[224:227], v[8:11]
	v_mfma_f32_16x16x32_bf16 v[52:55], v[152:155], v[228:231], v[52:55]
	s_waitcnt vmcnt(0)
	ds_read_b128 v[124:127], v246
	ds_read_b128 v[128:131], v246 offset:2048
	ds_read_b128 v[132:135], v246 offset:4096
	ds_read_b128 v[136:139], v246 offset:6144
	ds_read_b128 v[200:203], v246 offset:8192
	ds_read_b128 v[204:207], v246 offset:10240
	ds_read_b128 v[208:211], v246 offset:12288
	ds_read_b128 v[212:215], v246 offset:14336
	ds_read_b128 v[140:143], v247
	ds_read_b128 v[144:147], v247 offset:2048
	ds_read_b128 v[148:151], v247 offset:4096
	ds_read_b128 v[152:155], v247 offset:6144
	ds_read_b128 v[216:219], v247 offset:8192
	ds_read_b128 v[220:223], v247 offset:10240
	ds_read_b128 v[224:227], v247 offset:12288
	ds_read_b128 v[228:231], v247 offset:14336
	s_waitcnt lgkmcnt(0)
	v_mfma_f32_16x16x32_bf16 v[60:63], v[124:127], v[200:203], v[60:63]
	v_mfma_f32_16x16x32_bf16 v[56:59], v[124:127], v[204:207], v[56:59]
	v_mfma_f32_16x16x32_bf16 v[48:51], v[124:127], v[208:211], v[48:51]
	v_mfma_f32_16x16x32_bf16 v[44:47], v[124:127], v[212:215], v[44:47]
	v_mfma_f32_16x16x32_bf16 v[40:43], v[128:131], v[200:203], v[40:43]
	v_mfma_f32_16x16x32_bf16 v[36:39], v[128:131], v[204:207], v[36:39]
	v_mfma_f32_16x16x32_bf16 v[20:23], v[128:131], v[208:211], v[20:23]
	v_mfma_f32_16x16x32_bf16 v[12:15], v[128:131], v[212:215], v[12:15]
	v_mfma_f32_16x16x32_bf16 v[16:19], v[132:135], v[200:203], v[16:19]
	v_mfma_f32_16x16x32_bf16 v[24:27], v[132:135], v[204:207], v[24:27]
	v_mfma_f32_16x16x32_bf16 v[28:31], v[132:135], v[208:211], v[28:31]
	v_mfma_f32_16x16x32_bf16 v[32:35], v[132:135], v[212:215], v[32:35]
	v_mfma_f32_16x16x32_bf16 v[0:3], v[136:139], v[200:203], v[0:3]
	v_mfma_f32_16x16x32_bf16 v[4:7], v[136:139], v[204:207], v[4:7]
	v_mfma_f32_16x16x32_bf16 v[8:11], v[136:139], v[208:211], v[8:11]
	v_mfma_f32_16x16x32_bf16 v[52:55], v[136:139], v[212:215], v[52:55]
	v_mfma_f32_16x16x32_bf16 v[60:63], v[140:143], v[216:219], v[60:63]
	v_mfma_f32_16x16x32_bf16 v[56:59], v[140:143], v[220:223], v[56:59]
	v_mfma_f32_16x16x32_bf16 v[48:51], v[140:143], v[224:227], v[48:51]
	v_mfma_f32_16x16x32_bf16 v[44:47], v[140:143], v[228:231], v[44:47]
	v_mfma_f32_16x16x32_bf16 v[40:43], v[144:147], v[216:219], v[40:43]
	v_mfma_f32_16x16x32_bf16 v[36:39], v[144:147], v[220:223], v[36:39]
	v_mfma_f32_16x16x32_bf16 v[20:23], v[144:147], v[224:227], v[20:23]
	v_mfma_f32_16x16x32_bf16 v[12:15], v[144:147], v[228:231], v[12:15]
	v_mfma_f32_16x16x32_bf16 v[16:19], v[148:151], v[216:219], v[16:19]
	v_mfma_f32_16x16x32_bf16 v[24:27], v[148:151], v[220:223], v[24:27]
	v_mfma_f32_16x16x32_bf16 v[28:31], v[148:151], v[224:227], v[28:31]
	v_mfma_f32_16x16x32_bf16 v[32:35], v[148:151], v[228:231], v[32:35]
	v_mfma_f32_16x16x32_bf16 v[0:3], v[152:155], v[216:219], v[0:3]
	v_mfma_f32_16x16x32_bf16 v[4:7], v[152:155], v[220:223], v[4:7]
	v_mfma_f32_16x16x32_bf16 v[8:11], v[152:155], v[224:227], v[8:11]
	v_mfma_f32_16x16x32_bf16 v[52:55], v[152:155], v[228:231], v[52:55]
	s_movk_i32 s0, 0x200
	s_mov_b32 s1, 0
	s_cmpk_eq_i32 s0, 0x200
	s_waitcnt lgkmcnt(0)
	s_barrier
; template <int NH>
; __device__ void gemm_sample_rows(const Params& p, const u16* __restrict__ A, const u16* __restrict__ Bt,
;                                  const float* __restrict__ resid, float* __restrict__ outf, unsigned char* smem, const int rep) {
;     ...
;     __syncthreads();
;     {
;       const int h = (w * 256) / (K / NH);
; #pragma unroll
;       for (int mf = 0; mf < 4; ++mf)
; #pragma unroll
;         for (int r = 0; r < 4; ++r) {
;           const int row = mf * 16 + 4 * g + r;
;           const float sc = rstdS[row * NH + h];
; #pragma unroll
;           for (int nf = 0; nf < 4; ++nf) red[(w * 64 + row) * RS + nf * 16 + l15] = acc[mf][nf][r] * sc;
;         }
;     }
;     __syncthreads();
;     {
;       const int row = tid >> 3, c0 = (tid & 7) * 8;
;       float o[8];
;       const size_t gidx = (size_t)(m0 + row) * 1024 + n0 + c0;
	ds_read_b32 v68, v91
	s_lshl_b32 s0, s26, 6
	s_and_b32 s0, s0, 0x3c0
	s_add_i32 s26, s26, s96
	s_add_i32 s13, s13, s14
	s_waitcnt lgkmcnt(0)
	v_mul_f32_e32 v60, v60, v68
	v_mul_f32_e32 v56, v56, v68
	v_mul_f32_e32 v48, v48, v68
	v_mul_f32_e32 v44, v44, v68
	ds_write2_b32 v92, v60, v56 offset1:16
	ds_write2_b32 v92, v48, v44 offset0:32 offset1:48
	ds_read_b32 v44, v93
	s_add_i32 s15, s15, s16
	s_cmp_ge_i32 s26, s12
	s_waitcnt lgkmcnt(0)
	v_mul_f32_e32 v48, v61, v44
	v_mul_f32_e32 v56, v57, v44
	ds_write2_b32 v94, v48, v56 offset1:16
	v_mul_f32_e32 v48, v49, v44
	v_mul_f32_e32 v44, v45, v44
	ds_write2_b32 v94, v48, v44 offset0:32 offset1:48
	ds_read_b32 v44, v95
	s_waitcnt lgkmcnt(0)
	v_mul_f32_e32 v45, v62, v44
	v_mul_f32_e32 v48, v58, v44
	ds_write2_b32 v96, v45, v48 offset1:16
	v_mul_f32_e32 v45, v50, v44
	v_mul_f32_e32 v44, v46, v44
	ds_write2_b32 v96, v45, v44 offset0:32 offset1:48
	ds_read_b32 v44, v97
	s_waitcnt lgkmcnt(0)
	v_mul_f32_e32 v45, v63, v44
	v_mul_f32_e32 v46, v59, v44
	ds_write2_b32 v98, v45, v46 offset1:16
	v_mul_f32_e32 v45, v51, v44
	v_mul_f32_e32 v44, v47, v44
	ds_write2_b32 v98, v45, v44 offset0:32 offset1:48
	ds_read_b32 v44, v99
	s_waitcnt lgkmcnt(0)
	v_mul_f32_e32 v40, v40, v44
	v_mul_f32_e32 v36, v36, v44
	v_mul_f32_e32 v20, v20, v44
	v_mul_f32_e32 v12, v12, v44
	ds_write2_b32 v100, v40, v36 offset1:16
	ds_write2_b32 v100, v20, v12 offset0:32 offset1:48
	ds_read_b32 v12, v101
	v_add_u32_e32 v40, 0xc318, v65
	s_waitcnt lgkmcnt(0)
	v_mul_f32_e32 v20, v41, v12
	v_mul_f32_e32 v36, v37, v12
	ds_write2_b32 v102, v20, v36 offset1:16
	v_mul_f32_e32 v20, v21, v12
	v_mul_f32_e32 v12, v13, v12
	ds_write2_b32 v102, v20, v12 offset0:32 offset1:48
	ds_read_b32 v12, v103
	v_add_u32_e32 v36, 0x4118, v65
	s_waitcnt lgkmcnt(0)
	v_mul_f32_e32 v13, v42, v12
	v_mul_f32_e32 v20, v38, v12
	ds_write2_b32 v104, v13, v20 offset1:16
	v_mul_f32_e32 v13, v22, v12
	v_mul_f32_e32 v12, v14, v12
	ds_write2_b32 v104, v13, v12 offset0:32 offset1:48
	ds_read_b32 v12, v105
	v_add_u32_e32 v20, 0xc308, v65
	v_add_u32_e32 v22, 0x4110, v65
	v_add_u32_e32 v38, 0x8218, v65
	s_waitcnt lgkmcnt(0)
	v_mul_f32_e32 v13, v43, v12
	v_mul_f32_e32 v14, v39, v12
	ds_write2_b32 v106, v13, v14 offset1:16
	v_mul_f32_e32 v13, v23, v12
	v_mul_f32_e32 v12, v15, v12
	ds_write2_b32 v106, v13, v12 offset0:32 offset1:48
	ds_read_b32 v12, v107
	s_waitcnt lgkmcnt(0)
	v_mul_f32_e32 v13, v16, v12
	v_mul_f32_e32 v14, v24, v12
	ds_write2_b32 v108, v13, v14 offset1:16
	v_mul_f32_e32 v13, v28, v12
	v_mul_f32_e32 v12, v32, v12
	ds_write2_b32 v108, v13, v12 offset0:32 offset1:48
	ds_read_b32 v12, v109
	v_add_u32_e32 v16, 0x4108, v65
	v_add_u32_e32 v24, 0x8210, v65
	s_waitcnt lgkmcnt(0)
	v_mul_f32_e32 v13, v17, v12
	v_mul_f32_e32 v14, v25, v12
	ds_write2_b32 v110, v13, v14 offset1:16
	v_mul_f32_e32 v13, v29, v12
	v_mul_f32_e32 v12, v33, v12
	ds_write2_b32 v110, v13, v12 offset0:32 offset1:48
	ds_read_b32 v12, v111
	s_waitcnt lgkmcnt(0)
	v_mul_f32_e32 v13, v18, v12
	v_mul_f32_e32 v14, v26, v12
	ds_write2_b32 v112, v13, v14 offset1:16
	v_mul_f32_e32 v13, v30, v12
	v_mul_f32_e32 v12, v34, v12
	ds_write2_b32 v112, v13, v12 offset0:32 offset1:48
	ds_read_b32 v12, v113
	v_add_u32_e32 v18, 0x8208, v65
	v_add_u32_e32 v34, 0xc310, v65
	s_waitcnt lgkmcnt(0)
	v_mul_f32_e32 v13, v19, v12
	v_mul_f32_e32 v14, v27, v12
	ds_write2_b32 v114, v13, v14 offset1:16
	v_mul_f32_e32 v13, v31, v12
	v_mul_f32_e32 v12, v35, v12
	ds_write2_b32 v114, v13, v12 offset0:32 offset1:48
	ds_read_b32 v12, v115
	v_add_u32_e32 v14, 0xc300, v65
	s_waitcnt lgkmcnt(0)
	v_mul_f32_e32 v0, v0, v12
	v_mul_f32_e32 v4, v4, v12
	ds_write2_b32 v116, v0, v4 offset1:16
	v_mul_f32_e32 v0, v8, v12
	v_mul_f32_e32 v4, v52, v12
	ds_write2_b32 v116, v0, v4 offset0:32 offset1:48
	ds_read_b32 v0, v117
	v_add_u32_e32 v12, 0x8200, v65
	s_waitcnt lgkmcnt(0)
	v_mul_f32_e32 v1, v1, v0
	v_mul_f32_e32 v4, v5, v0
	ds_write2_b32 v118, v1, v4 offset1:16
	v_mul_f32_e32 v1, v9, v0
	v_mul_f32_e32 v0, v53, v0
	ds_write2_b32 v118, v1, v0 offset0:32 offset1:48
	ds_read_b32 v0, v119
	s_waitcnt lgkmcnt(0)
	v_mul_f32_e32 v1, v2, v0
	v_mul_f32_e32 v2, v6, v0
	ds_write2_b32 v120, v1, v2 offset1:16
	v_mul_f32_e32 v1, v10, v0
	v_mul_f32_e32 v0, v54, v0
	ds_write2_b32 v120, v1, v0 offset0:32 offset1:48
	ds_read_b32 v0, v121
	s_waitcnt lgkmcnt(0)
	v_mul_f32_e32 v1, v3, v0
	v_mul_f32_e32 v2, v7, v0
	ds_write2_b32 v122, v1, v2 offset1:16
	v_mul_f32_e32 v1, v11, v0
	v_mul_f32_e32 v0, v55, v0
	ds_write2_b32 v122, v1, v0 offset0:32 offset1:48
	v_add_u32_e32 v0, s27, v197
	v_ashrrev_i32_e32 v1, 31, v0
	v_lshlrev_b64 v[0:1], 10, v[0:1]
	v_or_b32_e32 v0, s0, v0
	v_or_b32_e32 v0, v0, v64
	v_lshlrev_b64 v[8:9], 2, v[0:1]
	v_lshl_add_u64 v[10:11], s[6:7], 0, v[8:9]
	s_waitcnt lgkmcnt(0)
	s_barrier
; template <int NH>
; __device__ void gemm_sample_rows(const Params& p, const u16* __restrict__ A, const u16* __restrict__ Bt,
;                                  const float* __restrict__ resid, float* __restrict__ outf, unsigned char* smem, const int rep) {
;     ...
;     {
;       const int row = tid >> 3, c0 = (tid & 7) * 8;
;       float o[8];
;       const size_t gidx = (size_t)(m0 + row) * 1024 + n0 + c0;
;       const float* rp = resid ? resid + gidx : p.x_sample + (size_t)(m0 - NPROMPT + row) * 1024 + n0 + c0;
;       const float4 r0 = *(const float4*)rp, r1 = *(const float4*)(rp + 4);
;       o[0] = r0.x; o[1] = r0.y; o[2] = r0.z; o[3] = r0.w; o[4] = r1.x; o[5] = r1.y; o[6] = r1.z; o[7] = r1.w;
; #pragma unroll
;       for (int ww = 0; ww < 8; ++ww)
; #pragma unroll
;         for (int j = 0; j < 8; ++j) o[j] += red[(ww * 64 + row) * RS + c0 + j];
;       *(float4*)(outf + gidx) = make_float4(o[0], o[1], o[2], o[3]);
;       *(float4*)(outf + gidx + 4) = make_float4(o[4], o[5], o[6], o[7]);
;     }
;     __syncthreads();
	global_load_dwordx4 v[0:3], v[10:11], off
	global_load_dwordx4 v[4:7], v[10:11], off offset:16
	v_add_u32_e32 v10, 0x4100, v65
	ds_read2_b32 v[10:11], v10 offset1:1
	ds_read2_b32 v[12:13], v12 offset1:1
	ds_read2_b32 v[14:15], v14 offset1:1
	ds_read2_b32 v[16:17], v16 offset1:1
	ds_read2_b32 v[18:19], v18 offset1:1
	ds_read2_b32 v[20:21], v20 offset1:1
	ds_read2_b32 v[22:23], v22 offset1:1
	ds_read2_b32 v[24:25], v24 offset1:1
	ds_read2_b32 v[26:27], v65 offset1:1
	ds_read2_b32 v[28:29], v65 offset0:2 offset1:3
	ds_read2_b32 v[30:31], v65 offset0:4 offset1:5
	ds_read2_b32 v[32:33], v65 offset0:6 offset1:7
	ds_read2_b32 v[34:35], v34 offset1:1
	ds_read2_b32 v[36:37], v36 offset1:1
	ds_read2_b32 v[38:39], v38 offset1:1
	ds_read2_b32 v[40:41], v40 offset1:1
	ds_read2_b32 v[42:43], v72 offset1:1
	ds_read2_b32 v[44:45], v73 offset1:1
	ds_read2_b32 v[46:47], v74 offset1:1
	ds_read2_b32 v[48:49], v75 offset1:1
	ds_read2_b32 v[50:51], v76 offset1:1
	ds_read2_b32 v[52:53], v77 offset1:1
	ds_read2_b32 v[54:55], v78 offset1:1
	ds_read2_b32 v[56:57], v79 offset1:1
	ds_read2_b32 v[58:59], v80 offset1:1
	ds_read2_b32 v[60:61], v81 offset1:1
	ds_read2_b32 v[62:63], v82 offset1:1
	ds_read2_b32 v[68:69], v83 offset1:1
	ds_read2_b32 v[70:71], v84 offset1:1
	ds_read2_b32 v[124:125], v85 offset1:1
	ds_read2_b32 v[126:127], v86 offset1:1
	ds_read2_b32 v[128:129], v87 offset1:1
	v_lshl_add_u64 v[8:9], s[8:9], 0, v[8:9]
	s_waitcnt vmcnt(1) lgkmcnt(14)
	v_pk_add_f32 v[0:1], v[0:1], v[26:27]
	v_pk_add_f32 v[2:3], v[2:3], v[28:29]
	v_pk_add_f32 v[0:1], v[0:1], v[10:11]
	v_pk_add_f32 v[2:3], v[2:3], v[16:17]
	v_pk_add_f32 v[0:1], v[0:1], v[12:13]
	v_pk_add_f32 v[2:3], v[2:3], v[18:19]
	v_pk_add_f32 v[0:1], v[0:1], v[14:15]
	v_pk_add_f32 v[2:3], v[2:3], v[20:21]
	v_pk_add_f32 v[0:1], v[0:1], v[42:43]
	v_pk_add_f32 v[2:3], v[2:3], v[44:45]
	s_waitcnt lgkmcnt(11)
	v_pk_add_f32 v[0:1], v[0:1], v[50:51]
	s_waitcnt lgkmcnt(10)
	v_pk_add_f32 v[2:3], v[2:3], v[52:53]
	s_waitcnt lgkmcnt(7)
	v_pk_add_f32 v[0:1], v[0:1], v[58:59]
	s_waitcnt lgkmcnt(6)
	v_pk_add_f32 v[2:3], v[2:3], v[60:61]
	s_waitcnt vmcnt(0)
	v_pk_add_f32 v[4:5], v[4:5], v[30:31]
	v_pk_add_f32 v[6:7], v[6:7], v[32:33]
	s_waitcnt lgkmcnt(3)
	v_pk_add_f32 v[0:1], v[0:1], v[70:71]
	s_waitcnt lgkmcnt(2)
	v_pk_add_f32 v[2:3], v[2:3], v[124:125]
	v_pk_add_f32 v[4:5], v[4:5], v[22:23]
	global_store_dwordx4 v[8:9], v[0:3], off
	v_pk_add_f32 v[4:5], v[4:5], v[24:25]
	s_nop 0
	v_pk_add_f32 v[0:1], v[6:7], v[36:37]
	v_pk_add_f32 v[4:5], v[4:5], v[34:35]
	v_pk_add_f32 v[0:1], v[0:1], v[38:39]
	v_pk_add_f32 v[4:5], v[4:5], v[46:47]
	v_pk_add_f32 v[0:1], v[0:1], v[40:41]
	v_pk_add_f32 v[4:5], v[4:5], v[54:55]
	v_pk_add_f32 v[0:1], v[0:1], v[48:49]
	v_pk_add_f32 v[4:5], v[4:5], v[62:63]
	v_pk_add_f32 v[0:1], v[0:1], v[56:57]
	s_waitcnt lgkmcnt(1)
	v_pk_add_f32 v[4:5], v[4:5], v[126:127]
	v_pk_add_f32 v[0:1], v[0:1], v[68:69]
	s_waitcnt lgkmcnt(0)
	v_pk_add_f32 v[6:7], v[0:1], v[128:129]
	global_store_dwordx4 v[8:9], v[4:7], off offset:16
	s_barrier
	s_cbranch_scc0 .LBB0_2031
